# hazard-pad pruning: removed the 12 removable post-inline-asm s_nop 0 pads inside the attention v_max3 chain
# baseline (speedup 1.0000x reference)
; __device__ __forceinline__ int crow(int r, int hi) { return (r & 3) + 8 * (r >> 2) + 4 * hi; }
; __device__ __forceinline__ float max3f(float a, float b, float c) { float r; asm("v_max3_f32 %0, %1, %2, %3" : "=v"(r) : "v"(a), "v"(b), "v"(c)); return r; }
; template <int THRL>
; __device__ __forceinline__ void attn_item(int b, int h, int s, const bf16_t* Q, const bf16_t* KN, const bf16_t* KR, const bf16_t* V, const float* goa  , bf16_t* Y, float* ssqy, AT_LAS char* shm, int wid0) {
;     ...
;                 float ma = max3f(p0[0], p0[1], p1[0]), mb = max3f(p0[2], p0[3], p1[1]); ma = max3f(ma, p1[2], p1[3]);
; #pragma unroll
;                 for (int r = 4; r < 16; r += 4) { ma = max3f(ma, p0[r], p0[r + 1]); mb = max3f(mb, p0[r + 2], p0[r + 3]); ma = max3f(ma, p1[r], p1[r + 1]); mb = max3f(mb, p1[r + 2], p1[r + 3]); }
;                 float rm = fmaxf(ma, mb);
;                 { auto rr = __builtin_amdgcn_permlane32_swap(__float_as_uint(rm), __float_as_uint(rm), false, false); rm = fmaxf(__uint_as_float(rr[0]), __uint_as_float(rr[1])); }
;                 if (t == 0 || __any(rm > (float)THRL)) {
;                     const float dl = (t == 0) ? rm : fmaxf(rm, 0.f); mhat += dl;
; #pragma unroll
;                     for (int r = 0; r < 16; ++r) { p0[r] -= dl; p1[r] -= dl; negm[r] = -mhat; }
;                     asm volatile("" : "+v"(negm));
;                     if (t > 0) { const float f = __builtin_amdgcn_exp2f(-dl); l_reg *= f; if (hi == 0) wsf[r32] = f; asm volatile("s_waitcnt lgkmcnt(0)" ::: "memory");
; #pragma unroll
;                         for (int r = 0; r < 16; ++r) { const float fr_ = wsf[crow(r, hi)]; o[0][r] *= fr_; o[1][r] *= fr_; } }
.LBB13_775:
	v_max3_f32 v0, v18, v19, v34
	v_max3_f32 v106, v20, v21, v35
	s_mov_b32 s88, 0x41000000
	v_max3_f32 v0, v0, v36, v37
	v_max3_f32 v106, v106, v24, v25
	v_max3_f32 v0, v0, v22, v23
	v_max3_f32 v106, v106, v40, v41
	v_max3_f32 v0, v0, v38, v39
	v_max3_f32 v106, v106, v28, v29
	v_max3_f32 v0, v0, v26, v27
	v_max3_f32 v106, v106, v44, v45
	v_max3_f32 v0, v0, v42, v43
	v_max3_f32 v106, v106, v32, v33
	v_max3_f32 v0, v0, v30, v31
	v_max3_f32 v106, v106, v48, v49
	v_max3_f32 v0, v0, v46, v47
	v_max_f32_e32 v106, v106, v106
	v_max_f32_e32 v0, v0, v0
	v_max_f32_e32 v0, v0, v106
	v_mov_b32_e32 v106, v0
	s_nop 1
	v_permlane32_swap_b32_e32 v0, v106
	v_max_f32_e32 v106, v106, v106
	v_max_f32_e32 v0, v0, v0
	v_max_f32_e32 v0, v0, v106
	v_cmp_lt_f32_e32 vcc, s88, v0
	s_cbranch_vccz .LBB13_779
	v_max_f32_e32 v0, v0, v0
	v_max_f32_e32 v0, 0, v0
	v_exp_f32_e64 v106, -v0
	v_add_f32_e32 v152, v152, v0
	v_xor_b32_e32 v66, 0x80000000, v152
	v_mov_b32_e32 v67, v66
	v_mov_b32_e32 v68, v66
	v_mov_b32_e32 v69, v66
	v_mov_b32_e32 v70, v66
	v_mov_b32_e32 v71, v66
	v_mov_b32_e32 v72, v66
	v_mov_b32_e32 v73, v66
	v_mov_b32_e32 v74, v66
	v_mov_b32_e32 v75, v66
	v_mov_b32_e32 v76, v66
	v_mov_b32_e32 v77, v66
	v_mov_b32_e32 v78, v66
	v_mov_b32_e32 v79, v66
	v_mov_b32_e32 v80, v66
	v_mov_b32_e32 v81, v66
	s_and_saveexec_b64 s[92:93], s[6:7]
	ds_write_b32 v193, v106
	s_or_b64 exec, exec, s[92:93]
	s_waitcnt lgkmcnt(0)
	v_mul_f32_e32 v153, v153, v106
	ds_read_b128 v[106:109], v194
	ds_read_b128 v[110:113], v194 offset:32
	ds_read_b128 v[114:117], v194 offset:64
	ds_read_b128 v[118:121], v194 offset:96
	v_pk_add_f32 v[18:19], v[18:19], v[0:1] op_sel_hi:[1,0] neg_lo:[0,1] neg_hi:[0,1]
	v_pk_add_f32 v[34:35], v[34:35], v[0:1] op_sel_hi:[1,0] neg_lo:[0,1] neg_hi:[0,1]
	v_pk_add_f32 v[20:21], v[20:21], v[0:1] op_sel_hi:[1,0] neg_lo:[0,1] neg_hi:[0,1]
	v_pk_add_f32 v[36:37], v[36:37], v[0:1] op_sel_hi:[1,0] neg_lo:[0,1] neg_hi:[0,1]
	v_pk_add_f32 v[22:23], v[22:23], v[0:1] op_sel_hi:[1,0] neg_lo:[0,1] neg_hi:[0,1]
	v_pk_add_f32 v[38:39], v[38:39], v[0:1] op_sel_hi:[1,0] neg_lo:[0,1] neg_hi:[0,1]
	v_pk_add_f32 v[24:25], v[24:25], v[0:1] op_sel_hi:[1,0] neg_lo:[0,1] neg_hi:[0,1]
	v_pk_add_f32 v[40:41], v[40:41], v[0:1] op_sel_hi:[1,0] neg_lo:[0,1] neg_hi:[0,1]
	v_pk_add_f32 v[26:27], v[26:27], v[0:1] op_sel_hi:[1,0] neg_lo:[0,1] neg_hi:[0,1]
	v_pk_add_f32 v[42:43], v[42:43], v[0:1] op_sel_hi:[1,0] neg_lo:[0,1] neg_hi:[0,1]
	v_pk_add_f32 v[28:29], v[28:29], v[0:1] op_sel_hi:[1,0] neg_lo:[0,1] neg_hi:[0,1]
	v_pk_add_f32 v[44:45], v[44:45], v[0:1] op_sel_hi:[1,0] neg_lo:[0,1] neg_hi:[0,1]
	v_pk_add_f32 v[30:31], v[30:31], v[0:1] op_sel_hi:[1,0] neg_lo:[0,1] neg_hi:[0,1]
	v_pk_add_f32 v[46:47], v[46:47], v[0:1] op_sel_hi:[1,0] neg_lo:[0,1] neg_hi:[0,1]
	v_pk_add_f32 v[32:33], v[32:33], v[0:1] op_sel_hi:[1,0] neg_lo:[0,1] neg_hi:[0,1]
	v_pk_add_f32 v[48:49], v[48:49], v[0:1] op_sel_hi:[1,0] neg_lo:[0,1] neg_hi:[0,1]
	s_waitcnt lgkmcnt(0)
	v_pk_mul_f32 v[64:65], v[64:65], v[120:121]
	v_pk_mul_f32 v[60:61], v[60:61], v[116:117]
	v_pk_mul_f32 v[56:57], v[56:57], v[112:113]
	v_pk_mul_f32 v[52:53], v[52:53], v[108:109]
	v_pk_mul_f32 v[62:63], v[62:63], v[118:119]
	v_pk_mul_f32 v[58:59], v[58:59], v[114:115]
	v_pk_mul_f32 v[54:55], v[54:55], v[110:111]
	v_pk_mul_f32 v[50:51], v[50:51], v[106:107]
	v_pk_mul_f32 v[16:17], v[16:17], v[120:121]
	v_pk_mul_f32 v[12:13], v[12:13], v[116:117]
	v_pk_mul_f32 v[8:9], v[8:9], v[112:113]
	v_pk_mul_f32 v[4:5], v[4:5], v[108:109]
	v_pk_mul_f32 v[14:15], v[14:15], v[118:119]
	v_pk_mul_f32 v[10:11], v[10:11], v[114:115]
	v_pk_mul_f32 v[6:7], v[6:7], v[110:111]
	v_pk_mul_f32 v[2:3], v[2:3], v[106:107]
